# k-loop re-pipelined, LDS-DMA source addresses computed before the barrier so that only m0 + load are issued after it
# speedup vs baseline: 1.0061x; 1.0061x over previous
; template <int EPI>
; __device__ __forceinline__ void gemm_tile(const bf16_t* __restrict__ A, const int lda, const bf16_t* __restrict__ Bt, const int ldb,
;                                           const int K, const int m0, const int n0, void* Cout, const int ldc, char* lds, const int tid) {
;     ...
;   for (int kt = 0; kt < nt; ++kt) {
;     asm volatile("s_waitcnt vmcnt(0)" ::: "memory");
;     __syncthreads();
;     if (kt + 1 < nt) stageB(kt + 1, (kt + 1) & 1);
;     const char* sa = lds + (kt & 1) * 32768;
;     const char* sb = sa + 16384;
;     bf16x8 af[2][4], bfr[2][4];
; #pragma unroll
;     for (int ks = 0; ks < 2; ++ks) {
; #pragma unroll
;       for (int m = 0; m < 4; ++m) af[ks][m] = *(const bf16x8*)(sa + (wr * 64 + m * 16 + fr) * 128 + (ks ? xk1 : xk0));
; #pragma unroll
;       for (int n = 0; n < 4; ++n) bfr[ks][n] = *(const bf16x8*)(sb + (wc * 64 + n * 16 + fr) * 128 + (ks ? xk1 : xk0));
;     }
;     if (kt + 1 < nt) stageA(kt + 1, (kt + 1) & 1);
; #pragma unroll
;     for (int ks = 0; ks < 2; ++ks)
; #pragma unroll
;       for (int m = 0; m < 4; ++m)
; #pragma unroll
;         for (int n = 0; n < 4; ++n) acc[m][n] = __builtin_amdgcn_mfma_f32_16x16x32_bf16(bfr[ks][n], af[ks][m], acc[m][n], 0, 0, 0);
;   }
.LBB0_104:
	s_add_i32 s25, s26, 0x8000
	s_and_b32 s23, s25, 0x8000
	s_and_b32 s26, s26, 0x8000
	s_waitcnt lgkmcnt(0)
	v_mfma_f32_16x16x32_bf16 v[64:67], v[190:193], v[104:107], v[64:67]
	v_or_b32_e32 v216, s26, v175
	v_add_u32_e32 v222, v216, v181
	v_mfma_f32_16x16x32_bf16 v[60:63], v[194:197], v[104:107], v[60:63]
	v_add_u32_e32 v224, v216, v180
	ds_read_b128 v[206:209], v222
	v_mfma_f32_16x16x32_bf16 v[56:59], v[198:201], v[104:107], v[56:59]
	ds_read_b128 v[210:213], v222 offset:2048
	ds_read_b128 v[92:95], v222 offset:4096
	v_mfma_f32_16x16x32_bf16 v[52:55], v[202:205], v[104:107], v[52:55]
	ds_read_b128 v[68:71], v222 offset:6144
	ds_read_b128 v[88:91], v224 offset:16384
	v_mfma_f32_16x16x32_bf16 v[36:39], v[190:193], v[100:103], v[36:39]
	ds_read_b128 v[80:83], v224 offset:18432
	ds_read_b128 v[72:75], v224 offset:20480
	v_mfma_f32_16x16x32_bf16 v[28:31], v[194:197], v[100:103], v[28:31]
	ds_read_b128 v[76:79], v224 offset:22528
	v_or_b32_e32 v214, s23, v174
	v_mfma_f32_16x16x32_bf16 v[20:23], v[198:201], v[100:103], v[20:23]
	v_add_u32_e32 v218, v214, v181
	v_add_u32_e32 v220, v214, v180
	v_mfma_f32_16x16x32_bf16 v[24:27], v[202:205], v[100:103], v[24:27]
	v_readfirstlane_b32 s100, v176
	s_add_i32 s100, s100, s26
	v_mfma_f32_16x16x32_bf16 v[8:11], v[190:193], v[96:99], v[8:11]
	s_add_u32 s62, s34, 0x80
	s_addc_u32 s63, s35, 0
	v_mfma_f32_16x16x32_bf16 v[16:19], v[194:197], v[96:99], v[16:19]
	v_lshl_add_u64 v[228:229], v[140:141], 0, s[62:63]
	v_lshl_add_u64 v[230:231], v[142:143], 0, s[62:63]
	v_mfma_f32_16x16x32_bf16 v[32:35], v[198:201], v[96:99], v[32:35]
	v_lshl_add_u64 v[232:233], v[144:145], 0, s[62:63]
	v_lshl_add_u64 v[234:235], v[146:147], 0, s[62:63]
	v_mfma_f32_16x16x32_bf16 v[48:51], v[202:205], v[96:99], v[48:51]
	v_lshl_add_u64 v[236:237], v[148:149], 0, s[62:63]
	v_lshl_add_u64 v[238:239], v[150:151], 0, s[62:63]
	v_mfma_f32_16x16x32_bf16 v[44:47], v[190:193], v[84:87], v[44:47]
	v_lshl_add_u64 v[226:227], v[152:153], 0, s[62:63]
	v_lshl_add_u64 v[250:251], v[154:155], 0, s[62:63]
	v_mfma_f32_16x16x32_bf16 v[40:43], v[194:197], v[84:87], v[40:43]
	v_mfma_f32_16x16x32_bf16 v[12:15], v[198:201], v[84:87], v[12:15]
	v_mfma_f32_16x16x32_bf16 v[4:7], v[202:205], v[84:87], v[4:7]
	s_waitcnt vmcnt(0) lgkmcnt(0)
	s_barrier
	s_cmpk_eq_i32 s34, 0x1500
	s_cbranch_scc1 .Lr_last_104
	v_mfma_f32_16x16x32_bf16 v[64:67], v[88:91], v[206:209], v[64:67]
	s_add_i32 m0, s100, 0x4000
	ds_read_b128 v[104:107], v218
	global_load_lds_dwordx4 v[228:229], off
	v_mfma_f32_16x16x32_bf16 v[60:63], v[80:83], v[206:209], v[60:63]
	s_add_i32 m0, s100, 0x5000
	ds_read_b128 v[100:103], v218 offset:2048
	global_load_lds_dwordx4 v[230:231], off
	v_mfma_f32_16x16x32_bf16 v[56:59], v[72:75], v[206:209], v[56:59]
	s_add_i32 m0, s100, 0x6000
	ds_read_b128 v[96:99], v218 offset:4096
	global_load_lds_dwordx4 v[232:233], off
	v_mfma_f32_16x16x32_bf16 v[52:55], v[76:79], v[206:209], v[52:55]
	s_add_i32 m0, s100, 0x7000
	ds_read_b128 v[84:87], v218 offset:6144
	global_load_lds_dwordx4 v[234:235], off
	v_mfma_f32_16x16x32_bf16 v[36:39], v[88:91], v[210:213], v[36:39]
	s_mov_b32 m0, s100
	ds_read_b128 v[190:193], v220 offset:16384
	global_load_lds_dwordx4 v[236:237], off
	v_mfma_f32_16x16x32_bf16 v[28:31], v[80:83], v[210:213], v[28:31]
	s_add_i32 m0, s100, 0x1000
	ds_read_b128 v[194:197], v220 offset:18432
	global_load_lds_dwordx4 v[238:239], off
	v_mfma_f32_16x16x32_bf16 v[20:23], v[72:75], v[210:213], v[20:23]
	s_add_i32 m0, s100, 0x2000
	ds_read_b128 v[198:201], v220 offset:20480
	global_load_lds_dwordx4 v[226:227], off
	v_mfma_f32_16x16x32_bf16 v[24:27], v[76:79], v[210:213], v[24:27]
	s_add_i32 m0, s100, 0x3000
	ds_read_b128 v[202:205], v220 offset:22528
	global_load_lds_dwordx4 v[250:251], off
	v_mfma_f32_16x16x32_bf16 v[8:11], v[88:91], v[92:95], v[8:11]
	v_mfma_f32_16x16x32_bf16 v[16:19], v[80:83], v[92:95], v[16:19]
	v_mfma_f32_16x16x32_bf16 v[32:35], v[72:75], v[92:95], v[32:35]
	v_mfma_f32_16x16x32_bf16 v[48:51], v[76:79], v[92:95], v[48:51]
	v_mfma_f32_16x16x32_bf16 v[44:47], v[88:91], v[68:71], v[44:47]
	v_mfma_f32_16x16x32_bf16 v[40:43], v[80:83], v[68:71], v[40:43]
	v_mfma_f32_16x16x32_bf16 v[12:15], v[72:75], v[68:71], v[12:15]
	v_mfma_f32_16x16x32_bf16 v[4:7], v[76:79], v[68:71], v[4:7]
	s_add_u32 s34, s34, 0x80
	s_addc_u32 s35, s35, 0
	s_mov_b32 s26, s25
	s_branch .LBB0_104

; template <int EPI>
; __device__ __forceinline__ void gemm_tile(const bf16_t* __restrict__ A, const int lda, const bf16_t* __restrict__ Bt, const int ldb,
;                                           const int K, const int m0, const int n0, void* Cout, const int ldc, char* lds, const int tid) {
;     ...
;   for (int kt = 0; kt < nt; ++kt) {
;     asm volatile("s_waitcnt vmcnt(0)" ::: "memory");
;     __syncthreads();
;     if (kt + 1 < nt) stageB(kt + 1, (kt + 1) & 1);
;     const char* sa = lds + (kt & 1) * 32768;
;     const char* sb = sa + 16384;
;     bf16x8 af[2][4], bfr[2][4];
; #pragma unroll
;     for (int ks = 0; ks < 2; ++ks) {
; #pragma unroll
;       for (int m = 0; m < 4; ++m) af[ks][m] = *(const bf16x8*)(sa + (wr * 64 + m * 16 + fr) * 128 + (ks ? xk1 : xk0));
; #pragma unroll
;       for (int n = 0; n < 4; ++n) bfr[ks][n] = *(const bf16x8*)(sb + (wc * 64 + n * 16 + fr) * 128 + (ks ? xk1 : xk0));
;     }
;     if (kt + 1 < nt) stageA(kt + 1, (kt + 1) & 1);
; #pragma unroll
;     for (int ks = 0; ks < 2; ++ks)
; #pragma unroll
;       for (int m = 0; m < 4; ++m)
; #pragma unroll
;         for (int n = 0; n < 4; ++n) acc[m][n] = __builtin_amdgcn_mfma_f32_16x16x32_bf16(bfr[ks][n], af[ks][m], acc[m][n], 0, 0, 0);
;   }
.LBB0_111:
	s_add_i32 s26, s27, 0x8000
	s_and_b32 s29, s26, 0x8000
	s_and_b32 s27, s27, 0x8000
	s_waitcnt lgkmcnt(0)
	v_mfma_f32_16x16x32_bf16 v[64:67], v[184:187], v[104:107], v[64:67]
	v_or_b32_e32 v216, s27, v176
	v_add_u32_e32 v222, v216, v182
	v_mfma_f32_16x16x32_bf16 v[60:63], v[188:191], v[104:107], v[60:63]
	v_add_u32_e32 v224, v216, v181
	ds_read_b128 v[200:203], v222
	v_mfma_f32_16x16x32_bf16 v[56:59], v[192:195], v[104:107], v[56:59]
	ds_read_b128 v[204:207], v222 offset:2048
	ds_read_b128 v[92:95], v222 offset:4096
	v_mfma_f32_16x16x32_bf16 v[52:55], v[196:199], v[104:107], v[52:55]
	ds_read_b128 v[68:71], v222 offset:6144
	ds_read_b128 v[88:91], v224 offset:16384
	v_mfma_f32_16x16x32_bf16 v[48:51], v[184:187], v[100:103], v[48:51]
	ds_read_b128 v[80:83], v224 offset:18432
	ds_read_b128 v[72:75], v224 offset:20480
	v_mfma_f32_16x16x32_bf16 v[44:47], v[188:191], v[100:103], v[44:47]
	ds_read_b128 v[76:79], v224 offset:22528
	v_or_b32_e32 v214, s29, v175
	v_mfma_f32_16x16x32_bf16 v[36:39], v[192:195], v[100:103], v[36:39]
	v_add_u32_e32 v218, v214, v182
	v_add_u32_e32 v220, v214, v181
	v_mfma_f32_16x16x32_bf16 v[40:43], v[196:199], v[100:103], v[40:43]
	v_readfirstlane_b32 s100, v177
	s_add_i32 s100, s100, s27
	v_mfma_f32_16x16x32_bf16 v[32:35], v[184:187], v[96:99], v[32:35]
	s_add_u32 s62, s2, 0x80
	s_addc_u32 s63, s3, 0
	v_mfma_f32_16x16x32_bf16 v[24:27], v[188:191], v[96:99], v[24:27]
	v_lshl_add_u64 v[228:229], v[140:141], 0, s[62:63]
	v_lshl_add_u64 v[230:231], v[142:143], 0, s[62:63]
	v_mfma_f32_16x16x32_bf16 v[28:31], v[192:195], v[96:99], v[28:31]
	v_lshl_add_u64 v[232:233], v[144:145], 0, s[62:63]
	v_lshl_add_u64 v[234:235], v[146:147], 0, s[62:63]
	v_mfma_f32_16x16x32_bf16 v[20:23], v[196:199], v[96:99], v[20:23]
	v_lshl_add_u64 v[236:237], v[148:149], 0, s[62:63]
	v_lshl_add_u64 v[238:239], v[150:151], 0, s[62:63]
	v_mfma_f32_16x16x32_bf16 v[16:19], v[184:187], v[84:87], v[16:19]
	v_lshl_add_u64 v[226:227], v[152:153], 0, s[62:63]
	v_lshl_add_u64 v[250:251], v[154:155], 0, s[62:63]
	v_mfma_f32_16x16x32_bf16 v[12:15], v[188:191], v[84:87], v[12:15]
	v_mfma_f32_16x16x32_bf16 v[8:11], v[192:195], v[84:87], v[8:11]
	v_mfma_f32_16x16x32_bf16 v[4:7], v[196:199], v[84:87], v[4:7]
	s_waitcnt vmcnt(0) lgkmcnt(0)
	s_barrier
	s_cmpk_eq_i32 s2, 0x700
	s_cbranch_scc1 .Lr_last_111
	v_mfma_f32_16x16x32_bf16 v[64:67], v[88:91], v[200:203], v[64:67]
	s_add_i32 m0, s100, 0x4000
	ds_read_b128 v[104:107], v218
	global_load_lds_dwordx4 v[228:229], off
	v_mfma_f32_16x16x32_bf16 v[60:63], v[80:83], v[200:203], v[60:63]
	s_add_i32 m0, s100, 0x5000
	ds_read_b128 v[100:103], v218 offset:2048
	global_load_lds_dwordx4 v[230:231], off
	v_mfma_f32_16x16x32_bf16 v[56:59], v[72:75], v[200:203], v[56:59]
	s_add_i32 m0, s100, 0x6000
	ds_read_b128 v[96:99], v218 offset:4096
	global_load_lds_dwordx4 v[232:233], off
	v_mfma_f32_16x16x32_bf16 v[52:55], v[76:79], v[200:203], v[52:55]
	s_add_i32 m0, s100, 0x7000
	ds_read_b128 v[84:87], v218 offset:6144
	global_load_lds_dwordx4 v[234:235], off
	v_mfma_f32_16x16x32_bf16 v[48:51], v[88:91], v[204:207], v[48:51]
	s_mov_b32 m0, s100
	ds_read_b128 v[184:187], v220 offset:16384
	global_load_lds_dwordx4 v[236:237], off
	v_mfma_f32_16x16x32_bf16 v[44:47], v[80:83], v[204:207], v[44:47]
	s_add_i32 m0, s100, 0x1000
	ds_read_b128 v[188:191], v220 offset:18432
	global_load_lds_dwordx4 v[238:239], off
	v_mfma_f32_16x16x32_bf16 v[36:39], v[72:75], v[204:207], v[36:39]
	s_add_i32 m0, s100, 0x2000
	ds_read_b128 v[192:195], v220 offset:20480
	global_load_lds_dwordx4 v[226:227], off
	v_mfma_f32_16x16x32_bf16 v[40:43], v[76:79], v[204:207], v[40:43]
	s_add_i32 m0, s100, 0x3000
	ds_read_b128 v[196:199], v220 offset:22528
	global_load_lds_dwordx4 v[250:251], off
	v_mfma_f32_16x16x32_bf16 v[32:35], v[88:91], v[92:95], v[32:35]
	v_mfma_f32_16x16x32_bf16 v[24:27], v[80:83], v[92:95], v[24:27]
	v_mfma_f32_16x16x32_bf16 v[28:31], v[72:75], v[92:95], v[28:31]
	v_mfma_f32_16x16x32_bf16 v[20:23], v[76:79], v[92:95], v[20:23]
	v_mfma_f32_16x16x32_bf16 v[16:19], v[88:91], v[68:71], v[16:19]
	v_mfma_f32_16x16x32_bf16 v[12:15], v[80:83], v[68:71], v[12:15]
	v_mfma_f32_16x16x32_bf16 v[8:11], v[72:75], v[68:71], v[8:11]
	v_mfma_f32_16x16x32_bf16 v[4:7], v[76:79], v[68:71], v[4:7]
	s_add_u32 s2, s2, 0x80
	s_addc_u32 s3, s3, 0
	s_mov_b32 s27, s26
	s_branch .LBB0_111

; template <int EPI>
; __device__ __forceinline__ void gemm_tile(const bf16_t* __restrict__ A, const int lda, const bf16_t* __restrict__ Bt, const int ldb,
;                                           const int K, const int m0, const int n0, void* Cout, const int ldc, char* lds, const int tid) {
;     ...
;   for (int kt = 0; kt < nt; ++kt) {
;     asm volatile("s_waitcnt vmcnt(0)" ::: "memory");
;     __syncthreads();
;     if (kt + 1 < nt) stageB(kt + 1, (kt + 1) & 1);
;     const char* sa = lds + (kt & 1) * 32768;
;     const char* sb = sa + 16384;
;     bf16x8 af[2][4], bfr[2][4];
; #pragma unroll
;     for (int ks = 0; ks < 2; ++ks) {
; #pragma unroll
;       for (int m = 0; m < 4; ++m) af[ks][m] = *(const bf16x8*)(sa + (wr * 64 + m * 16 + fr) * 128 + (ks ? xk1 : xk0));
; #pragma unroll
;       for (int n = 0; n < 4; ++n) bfr[ks][n] = *(const bf16x8*)(sb + (wc * 64 + n * 16 + fr) * 128 + (ks ? xk1 : xk0));
;     }
;     if (kt + 1 < nt) stageA(kt + 1, (kt + 1) & 1);
; #pragma unroll
;     for (int ks = 0; ks < 2; ++ks)
; #pragma unroll
;       for (int m = 0; m < 4; ++m)
; #pragma unroll
;         for (int n = 0; n < 4; ++n) acc[m][n] = __builtin_amdgcn_mfma_f32_16x16x32_bf16(bfr[ks][n], af[ks][m], acc[m][n], 0, 0, 0);
;   }
.LBB0_125:
	s_add_i32 s25, s26, 0x8000
	s_and_b32 s23, s25, 0x8000
	s_and_b32 s26, s26, 0x8000
	s_waitcnt lgkmcnt(0)
	v_mfma_f32_16x16x32_bf16 v[64:67], v[184:187], v[104:107], v[64:67]
	v_or_b32_e32 v216, s26, v175
	v_add_u32_e32 v222, v216, v181
	v_mfma_f32_16x16x32_bf16 v[60:63], v[188:191], v[104:107], v[60:63]
	v_add_u32_e32 v224, v216, v180
	ds_read_b128 v[200:203], v222
	v_mfma_f32_16x16x32_bf16 v[56:59], v[192:195], v[104:107], v[56:59]
	ds_read_b128 v[204:207], v222 offset:2048
	ds_read_b128 v[92:95], v222 offset:4096
	v_mfma_f32_16x16x32_bf16 v[52:55], v[196:199], v[104:107], v[52:55]
	ds_read_b128 v[68:71], v222 offset:6144
	ds_read_b128 v[88:91], v224 offset:16384
	v_mfma_f32_16x16x32_bf16 v[36:39], v[184:187], v[100:103], v[36:39]
	ds_read_b128 v[80:83], v224 offset:18432
	ds_read_b128 v[72:75], v224 offset:20480
	v_mfma_f32_16x16x32_bf16 v[28:31], v[188:191], v[100:103], v[28:31]
	ds_read_b128 v[76:79], v224 offset:22528
	v_or_b32_e32 v214, s23, v174
	v_mfma_f32_16x16x32_bf16 v[20:23], v[192:195], v[100:103], v[20:23]
	v_add_u32_e32 v218, v214, v181
	v_add_u32_e32 v220, v214, v180
	v_mfma_f32_16x16x32_bf16 v[24:27], v[196:199], v[100:103], v[24:27]
	v_readfirstlane_b32 s100, v176
	s_add_i32 s100, s100, s26
	v_mfma_f32_16x16x32_bf16 v[8:11], v[184:187], v[96:99], v[8:11]
	s_add_u32 s62, s34, 0x80
	s_addc_u32 s63, s35, 0
	v_mfma_f32_16x16x32_bf16 v[16:19], v[188:191], v[96:99], v[16:19]
	v_lshl_add_u64 v[228:229], v[140:141], 0, s[62:63]
	v_lshl_add_u64 v[230:231], v[142:143], 0, s[62:63]
	v_mfma_f32_16x16x32_bf16 v[32:35], v[192:195], v[96:99], v[32:35]
	v_lshl_add_u64 v[232:233], v[144:145], 0, s[62:63]
	v_lshl_add_u64 v[234:235], v[146:147], 0, s[62:63]
	v_mfma_f32_16x16x32_bf16 v[48:51], v[196:199], v[96:99], v[48:51]
	v_lshl_add_u64 v[236:237], v[148:149], 0, s[62:63]
	v_lshl_add_u64 v[238:239], v[150:151], 0, s[62:63]
	v_mfma_f32_16x16x32_bf16 v[44:47], v[184:187], v[84:87], v[44:47]
	v_lshl_add_u64 v[226:227], v[152:153], 0, s[62:63]
	v_lshl_add_u64 v[250:251], v[154:155], 0, s[62:63]
	v_mfma_f32_16x16x32_bf16 v[40:43], v[188:191], v[84:87], v[40:43]
	v_mfma_f32_16x16x32_bf16 v[12:15], v[192:195], v[84:87], v[12:15]
	v_mfma_f32_16x16x32_bf16 v[4:7], v[196:199], v[84:87], v[4:7]
	s_waitcnt vmcnt(0) lgkmcnt(0)
	s_barrier
	s_cmpk_eq_i32 s34, 0x700
	s_cbranch_scc1 .Lr_last_125
	v_mfma_f32_16x16x32_bf16 v[64:67], v[88:91], v[200:203], v[64:67]
	s_add_i32 m0, s100, 0x4000
	ds_read_b128 v[104:107], v218
	global_load_lds_dwordx4 v[228:229], off
	v_mfma_f32_16x16x32_bf16 v[60:63], v[80:83], v[200:203], v[60:63]
	s_add_i32 m0, s100, 0x5000
	ds_read_b128 v[100:103], v218 offset:2048
	global_load_lds_dwordx4 v[230:231], off
	v_mfma_f32_16x16x32_bf16 v[56:59], v[72:75], v[200:203], v[56:59]
	s_add_i32 m0, s100, 0x6000
	ds_read_b128 v[96:99], v218 offset:4096
	global_load_lds_dwordx4 v[232:233], off
	v_mfma_f32_16x16x32_bf16 v[52:55], v[76:79], v[200:203], v[52:55]
	s_add_i32 m0, s100, 0x7000
	ds_read_b128 v[84:87], v218 offset:6144
	global_load_lds_dwordx4 v[234:235], off
	v_mfma_f32_16x16x32_bf16 v[36:39], v[88:91], v[204:207], v[36:39]
	s_mov_b32 m0, s100
	ds_read_b128 v[184:187], v220 offset:16384
	global_load_lds_dwordx4 v[236:237], off
	v_mfma_f32_16x16x32_bf16 v[28:31], v[80:83], v[204:207], v[28:31]
	s_add_i32 m0, s100, 0x1000
	ds_read_b128 v[188:191], v220 offset:18432
	global_load_lds_dwordx4 v[238:239], off
	v_mfma_f32_16x16x32_bf16 v[20:23], v[72:75], v[204:207], v[20:23]
	s_add_i32 m0, s100, 0x2000
	ds_read_b128 v[192:195], v220 offset:20480
	global_load_lds_dwordx4 v[226:227], off
	v_mfma_f32_16x16x32_bf16 v[24:27], v[76:79], v[204:207], v[24:27]
	s_add_i32 m0, s100, 0x3000
	ds_read_b128 v[196:199], v220 offset:22528
	global_load_lds_dwordx4 v[250:251], off
	v_mfma_f32_16x16x32_bf16 v[8:11], v[88:91], v[92:95], v[8:11]
	v_mfma_f32_16x16x32_bf16 v[16:19], v[80:83], v[92:95], v[16:19]
	v_mfma_f32_16x16x32_bf16 v[32:35], v[72:75], v[92:95], v[32:35]
	v_mfma_f32_16x16x32_bf16 v[48:51], v[76:79], v[92:95], v[48:51]
	v_mfma_f32_16x16x32_bf16 v[44:47], v[88:91], v[68:71], v[44:47]
	v_mfma_f32_16x16x32_bf16 v[40:43], v[80:83], v[68:71], v[40:43]
	v_mfma_f32_16x16x32_bf16 v[12:15], v[72:75], v[68:71], v[12:15]
	v_mfma_f32_16x16x32_bf16 v[4:7], v[76:79], v[68:71], v[4:7]
	s_add_u32 s34, s34, 0x80
	s_addc_u32 s35, s35, 0
	s_mov_b32 s26, s25
	s_branch .LBB0_125

; template <int EPI>
; __device__ __forceinline__ void gemm_tile(const bf16_t* __restrict__ A, const int lda, const bf16_t* __restrict__ Bt, const int ldb,
;                                           const int K, const int m0, const int n0, void* Cout, const int ldc, char* lds, const int tid) {
;     ...
;   for (int kt = 0; kt < nt; ++kt) {
;     asm volatile("s_waitcnt vmcnt(0)" ::: "memory");
;     __syncthreads();
;     if (kt + 1 < nt) stageB(kt + 1, (kt + 1) & 1);
;     const char* sa = lds + (kt & 1) * 32768;
;     const char* sb = sa + 16384;
;     bf16x8 af[2][4], bfr[2][4];
; #pragma unroll
;     for (int ks = 0; ks < 2; ++ks) {
; #pragma unroll
;       for (int m = 0; m < 4; ++m) af[ks][m] = *(const bf16x8*)(sa + (wr * 64 + m * 16 + fr) * 128 + (ks ? xk1 : xk0));
; #pragma unroll
;       for (int n = 0; n < 4; ++n) bfr[ks][n] = *(const bf16x8*)(sb + (wc * 64 + n * 16 + fr) * 128 + (ks ? xk1 : xk0));
;     }
;     if (kt + 1 < nt) stageA(kt + 1, (kt + 1) & 1);
; #pragma unroll
;     for (int ks = 0; ks < 2; ++ks)
; #pragma unroll
;       for (int m = 0; m < 4; ++m)
; #pragma unroll
;         for (int n = 0; n < 4; ++n) acc[m][n] = __builtin_amdgcn_mfma_f32_16x16x32_bf16(bfr[ks][n], af[ks][m], acc[m][n], 0, 0, 0);
;   }
.LBB0_649:
	s_add_i32 s24, s25, 0x8000
	s_and_b32 s26, s24, 0x8000
	s_and_b32 s25, s25, 0x8000
	s_waitcnt lgkmcnt(0)
	v_mfma_f32_16x16x32_bf16 v[64:67], v[184:187], v[104:107], v[64:67]
	v_or_b32_e32 v216, s25, v176
	v_add_u32_e32 v222, v216, v182
	v_mfma_f32_16x16x32_bf16 v[60:63], v[188:191], v[104:107], v[60:63]
	v_add_u32_e32 v224, v216, v181
	ds_read_b128 v[200:203], v222
	v_mfma_f32_16x16x32_bf16 v[56:59], v[192:195], v[104:107], v[56:59]
	ds_read_b128 v[204:207], v222 offset:2048
	ds_read_b128 v[92:95], v222 offset:4096
	v_mfma_f32_16x16x32_bf16 v[44:47], v[196:199], v[104:107], v[44:47]
	ds_read_b128 v[68:71], v222 offset:6144
	ds_read_b128 v[88:91], v224 offset:16384
	v_mfma_f32_16x16x32_bf16 v[36:39], v[184:187], v[100:103], v[36:39]
	ds_read_b128 v[80:83], v224 offset:18432
	ds_read_b128 v[72:75], v224 offset:20480
	v_mfma_f32_16x16x32_bf16 v[28:31], v[188:191], v[100:103], v[28:31]
	ds_read_b128 v[76:79], v224 offset:22528
	v_or_b32_e32 v214, s26, v175
	v_mfma_f32_16x16x32_bf16 v[12:15], v[192:195], v[100:103], v[12:15]
	v_add_u32_e32 v218, v214, v182
	v_add_u32_e32 v220, v214, v181
	v_mfma_f32_16x16x32_bf16 v[24:27], v[196:199], v[100:103], v[24:27]
	v_readfirstlane_b32 s100, v177
	s_add_i32 s100, s100, s25
	v_mfma_f32_16x16x32_bf16 v[8:11], v[184:187], v[96:99], v[8:11]
	s_add_u32 s62, s34, 0x80
	s_addc_u32 s63, s35, 0
	v_mfma_f32_16x16x32_bf16 v[20:23], v[188:191], v[96:99], v[20:23]
	v_lshl_add_u64 v[228:229], v[140:141], 0, s[62:63]
	v_lshl_add_u64 v[230:231], v[142:143], 0, s[62:63]
	v_mfma_f32_16x16x32_bf16 v[32:35], v[192:195], v[96:99], v[32:35]
	v_lshl_add_u64 v[232:233], v[144:145], 0, s[62:63]
	v_lshl_add_u64 v[234:235], v[146:147], 0, s[62:63]
	v_mfma_f32_16x16x32_bf16 v[52:55], v[196:199], v[96:99], v[52:55]
	v_lshl_add_u64 v[236:237], v[148:149], 0, s[62:63]
	v_lshl_add_u64 v[238:239], v[150:151], 0, s[62:63]
	v_mfma_f32_16x16x32_bf16 v[48:51], v[184:187], v[84:87], v[48:51]
	v_lshl_add_u64 v[226:227], v[152:153], 0, s[62:63]
	v_lshl_add_u64 v[250:251], v[154:155], 0, s[62:63]
	v_mfma_f32_16x16x32_bf16 v[40:43], v[188:191], v[84:87], v[40:43]
	v_mfma_f32_16x16x32_bf16 v[16:19], v[192:195], v[84:87], v[16:19]
	v_mfma_f32_16x16x32_bf16 v[4:7], v[196:199], v[84:87], v[4:7]
	s_waitcnt vmcnt(0) lgkmcnt(0)
	s_barrier
	s_cmpk_eq_i32 s34, 0x700
	s_cbranch_scc1 .Lr_last_649
	v_mfma_f32_16x16x32_bf16 v[64:67], v[88:91], v[200:203], v[64:67]
	s_add_i32 m0, s100, 0x4000
	ds_read_b128 v[104:107], v218
	global_load_lds_dwordx4 v[228:229], off
	v_mfma_f32_16x16x32_bf16 v[60:63], v[80:83], v[200:203], v[60:63]
	s_add_i32 m0, s100, 0x5000
	ds_read_b128 v[100:103], v218 offset:2048
	global_load_lds_dwordx4 v[230:231], off
	v_mfma_f32_16x16x32_bf16 v[56:59], v[72:75], v[200:203], v[56:59]
	s_add_i32 m0, s100, 0x6000
	ds_read_b128 v[96:99], v218 offset:4096
	global_load_lds_dwordx4 v[232:233], off
	v_mfma_f32_16x16x32_bf16 v[44:47], v[76:79], v[200:203], v[44:47]
	s_add_i32 m0, s100, 0x7000
	ds_read_b128 v[84:87], v218 offset:6144
	global_load_lds_dwordx4 v[234:235], off
	v_mfma_f32_16x16x32_bf16 v[36:39], v[88:91], v[204:207], v[36:39]
	s_mov_b32 m0, s100
	ds_read_b128 v[184:187], v220 offset:16384
	global_load_lds_dwordx4 v[236:237], off
	v_mfma_f32_16x16x32_bf16 v[28:31], v[80:83], v[204:207], v[28:31]
	s_add_i32 m0, s100, 0x1000
	ds_read_b128 v[188:191], v220 offset:18432
	global_load_lds_dwordx4 v[238:239], off
	v_mfma_f32_16x16x32_bf16 v[12:15], v[72:75], v[204:207], v[12:15]
	s_add_i32 m0, s100, 0x2000
	ds_read_b128 v[192:195], v220 offset:20480
	global_load_lds_dwordx4 v[226:227], off
	v_mfma_f32_16x16x32_bf16 v[24:27], v[76:79], v[204:207], v[24:27]
	s_add_i32 m0, s100, 0x3000
	ds_read_b128 v[196:199], v220 offset:22528
	global_load_lds_dwordx4 v[250:251], off
	v_mfma_f32_16x16x32_bf16 v[8:11], v[88:91], v[92:95], v[8:11]
	v_mfma_f32_16x16x32_bf16 v[20:23], v[80:83], v[92:95], v[20:23]
	v_mfma_f32_16x16x32_bf16 v[32:35], v[72:75], v[92:95], v[32:35]
	v_mfma_f32_16x16x32_bf16 v[52:55], v[76:79], v[92:95], v[52:55]
	v_mfma_f32_16x16x32_bf16 v[48:51], v[88:91], v[68:71], v[48:51]
	v_mfma_f32_16x16x32_bf16 v[40:43], v[80:83], v[68:71], v[40:43]
	v_mfma_f32_16x16x32_bf16 v[16:19], v[72:75], v[68:71], v[16:19]
	v_mfma_f32_16x16x32_bf16 v[4:7], v[76:79], v[68:71], v[4:7]
	s_add_u32 s34, s34, 0x80
	s_addc_u32 s35, s35, 0
	s_mov_b32 s25, s24
	s_branch .LBB0_649
